# v70 + code placement: P5 phase code moved by 32 bytes (pad behind the phase entry, 224-byte compensation at the next phase entry so later phases keep their placement); chosen by a repeat-amplified tim
# speedup vs baseline: 1.0110x; 1.0043x over previous
.LBB0_1363:
	s_nop 0
	s_nop 0
	s_nop 0
	s_nop 0
	s_nop 0
	s_nop 0
	s_nop 0
	s_nop 0
	s_cmp_lt_i32 s84, 6
	s_cselect_b64 s[0:1], -1, 0
	s_cmp_gt_i32 s85, 5
	s_cselect_b64 s[2:3], -1, 0
	s_and_b64 s[0:1], s[0:1], s[2:3]
	s_andn2_b64 vcc, exec, s[0:1]
	s_cbranch_vccnz .LBB0_1960
	v_lshrrev_b32_e32 v1, 2, v170
	v_lshrrev_b32_e32 v173, 3, v170
	v_and_b32_e32 v171, 15, v170
	s_cmpk_gt_i32 s86, 0xc5f
	v_readfirstlane_b32 s63, v170
	s_waitcnt lgkmcnt(0)
	s_barrier
	s_cbranch_scc1 .LBB0_1701
	s_add_u32 s65, s30, 0x1b800000
	s_addc_u32 s66, s31, 0
	s_add_u32 s67, s30, 0xa2d800
	s_waitcnt vmcnt(15)
	v_lshlrev_b32_e32 v4, 1, v1
	v_lshrrev_b32_e32 v5, 5, v170
	s_addc_u32 s68, s31, 0
	v_lshlrev_b32_e32 v2, 4, v170
	v_and_b32_e32 v3, 32, v170
	s_waitcnt vmcnt(13)
	v_and_b32_e32 v12, 15, v1
	v_and_b32_e32 v4, 24, v4
	v_and_b32_e32 v5, 4, v5
	v_and_b32_e32 v6, 3, v1
	s_movk_i32 s0, 0x70
	s_ashr_i32 s69, s86, 31
	v_bitop3_b32 v10, v2, v3, 48 bitop3:0x6c
	v_and_b32_e32 v11, 64, v170
	v_or3_b32 v4, v5, v6, v4
	v_and_or_b32 v5, v173, s0, v12
	s_movk_i32 s0, 0x60
	v_add_u32_e32 v13, 0x2000, v2
	s_lshr_b32 s2, s69, 29
	v_or_b32_e32 v3, v10, v11
	v_and_or_b32 v6, v173, s0, v4
	v_lshrrev_b32_e32 v2, 7, v13
	s_movk_i32 s0, 0xf0
	s_add_i32 s2, s86, s2
	v_lshl_or_b32 v162, v5, 11, v3
	v_and_or_b32 v5, v2, s0, v12
	s_movk_i32 s0, 0xe0
	s_and_b32 s1, s86, 15
	s_ashr_i32 s3, s2, 3
	s_and_b32 s2, s2, -8
	v_and_or_b32 v2, v2, s0, v4
	s_bfe_u32 s0, s86, 0x30004
	s_bitset1_b32 s1, 7
	s_sub_i32 s2, s86, s2
	s_cmp_lt_i32 s2, 0
	s_movk_i32 s70, 0x181
	s_cselect_b32 s4, s70, 0x180
	s_mul_i32 s2, s4, s2
	s_add_i32 s2, s2, s3
	s_mul_hi_i32 s3, s2, 0x2aaaaaab
	s_lshr_b32 s4, s3, 31
	s_ashr_i32 s3, s3, 5
	s_add_i32 s3, s3, s4
	s_lshl_b32 s4, s3, 3
	s_mulk_i32 s3, 0xc0
	s_sub_i32 s2, s2, s3
	s_bfe_u32 s3, s2, 0x3001c
	s_add_i32 s3, s2, s3
	s_sext_i32_i16 s5, s3
	s_and_b32 s3, s3, 0xfff8
	s_sub_i32 s2, s2, s3
	s_sext_i32_i16 s2, s2
	s_lshr_b32 s19, s63, 6
	s_add_i32 s4, s4, s2
	s_ashr_i32 s2, s5, 3
	s_lshr_b32 s18, s63, 8
	s_lshl_b32 s71, s19, 10
	s_add_i32 s3, s86, 0xfffff400
	s_cmpk_lt_u32 s3, 0x60
	s_cselect_b32 s2, s0, s2
	s_cselect_b32 s4, s1, s4
	s_ashr_i32 s5, s4, 31
	s_ashr_i32 s3, s2, 31
	s_lshl_b64 s[0:1], s[4:5], 19
	s_lshl_b64 s[6:7], s[2:3], 19
	s_add_u32 s54, s67, s6
	s_addc_u32 s55, s68, s7
	s_add_i32 s72, s71, 0
	v_lshl_or_b32 v164, v6, 11, v3
	s_add_i32 m0, s72, 0x10000
	v_lshl_or_b32 v168, v2, 11, v3
	global_load_lds_dwordx4 v164, s[54:55]
	s_add_i32 m0, s72, 0x12000
	s_add_u32 s34, s65, s0
	global_load_lds_dwordx4 v168, s[54:55]
	s_addc_u32 s35, s66, s1
	s_mov_b32 m0, s72
	s_add_i32 s73, s72, 0x2000
	v_lshl_or_b32 v166, v5, 11, v3
	global_load_lds_dwordx4 v162, s[34:35]
	s_mov_b32 m0, s73
	s_add_u32 s0, s54, 0x40000
	global_load_lds_dwordx4 v166, s[34:35]
	s_addc_u32 s1, s55, 0
	s_add_i32 m0, s72, 0x14000
	v_mov_b32_e32 v177, 0
	global_load_lds_dwordx4 v164, s[0:1]
	s_add_i32 m0, s72, 0x16000
	v_mov_b32_e32 v165, v177
	global_load_lds_dwordx4 v168, s[0:1]
	s_add_u32 s0, s34, 0x40000
	s_addc_u32 s1, s35, 0
	s_add_i32 s74, s72, 0x4000
	s_mov_b32 m0, s74
	s_add_i32 s75, s72, 0x6000
	global_load_lds_dwordx4 v162, s[0:1]
	s_mov_b32 m0, s75
	v_mov_b32_e32 v169, v177
	global_load_lds_dwordx4 v166, s[0:1]
	v_mov_b32_e32 v163, v177
	v_mov_b32_e32 v167, v177
	s_mov_b32 s62, s97
	s_mov_b32 s61, s96
	s_mov_b32 s76, 0
	v_lshl_add_u64 v[8:9], s[54:55], 0, v[164:165]
	v_lshl_add_u64 v[6:7], s[54:55], 0, v[168:169]
	v_lshl_add_u64 v[4:5], s[34:35], 0, v[162:163]
	s_cmp_lg_u32 s18, 1
	v_lshl_add_u64 v[2:3], s[34:35], 0, v[166:167]
	s_cbranch_scc1 .LBB0_1367
	s_barrier

.LBB0_1960:
	s_nop 0
	s_nop 0
	s_nop 0
	s_nop 0
	s_nop 0
	s_nop 0
	s_nop 0
	s_nop 0
	s_nop 0
	s_nop 0
	s_nop 0
	s_nop 0
	s_nop 0
	s_nop 0
	s_nop 0
	s_nop 0
	s_nop 0
	s_nop 0
	s_nop 0
	s_nop 0
	s_nop 0
	s_nop 0
	s_nop 0
	s_nop 0
	s_nop 0
	s_nop 0
	s_nop 0
	s_nop 0
	s_nop 0
	s_nop 0
	s_nop 0
	s_nop 0
	s_nop 0
	s_nop 0
	s_nop 0
	s_nop 0
	s_nop 0
	s_nop 0
	s_nop 0
	s_nop 0
	s_nop 0
	s_nop 0
	s_nop 0
	s_nop 0
	s_nop 0
	s_nop 0
	s_nop 0
	s_nop 0
	s_nop 0
	s_nop 0
	s_nop 0
	s_nop 0
	s_nop 0
	s_nop 0
	s_nop 0
	s_nop 0
	s_cmp_lt_i32 s84, 7
	s_cselect_b64 s[0:1], -1, 0
	s_cmp_gt_i32 s85, 6
	s_cselect_b64 s[2:3], -1, 0
	s_and_b64 s[0:1], s[0:1], s[2:3]
	s_andn2_b64 vcc, exec, s[0:1]
	s_cbranch_vccnz .LBB0_2004
	v_readlane_b32 s0, v254, 4
	v_readlane_b32 s1, v254, 5
	s_xor_b64 s[0:1], s[90:91], -1
	s_bfe_u32 s33, s86, 0x10004
	s_add_u32 s36, s30, 0x9b00000
	v_writelane_b32 v254, s0, 27
	s_addc_u32 s37, s31, 0
	s_add_u32 s38, s30, 0x10700000
	v_writelane_b32 v254, s1, 28
	s_addc_u32 s39, s31, 0
	v_readlane_b32 s0, v254, 1
	s_cmpk_gt_u32 s0, 0xff
	s_cselect_b64 s[40:41], -1, 0
	s_cmpk_lt_i32 s86, 0x100
	s_cselect_b64 s[48:49], -1, 0
	s_bfe_u32 s6, s0, 0x20006
	s_lshl_b32 s2, s6, 9
	s_lshl_b32 s34, s6, 4
	s_add_i32 s60, s2, 0
	s_xor_b32 s35, s34, 0xff
	s_xor_b32 s54, s34, 0xbf
	s_or_b32 s55, s34, 64
	s_xor_b32 s56, s34, 0x7f
	s_or_b32 s57, s34, 0x80
	s_add_i32 s60, s60, 0x1ec00
	s_cmp_eq_u32 s6, 0
	s_cselect_b64 s[50:51], -1, 0
	s_lshl_b32 s3, s88, 2
	s_and_b32 s2, s34, 32
	s_and_b32 s3, s3, 4
	s_or_b32 s10, s2, s3
	s_xor_b32 s61, s34, 63
	s_or_b32 s64, s34, 0xc0
	s_cmp_gt_u32 s6, 1
	s_cselect_b64 s[2:3], -1, 0
	s_cmp_eq_u32 s6, 3
	s_cselect_b64 s[4:5], -1, 0
	s_add_u32 s65, s28, 0x4000000
	s_addc_u32 s66, s29, 0
	s_add_u32 s67, s30, 0x14700000
	s_addc_u32 s68, s31, 0
	s_mul_i32 s11, s6, 0x880
	s_cmpk_lt_i32 s96, 0xc00
	s_cselect_b64 s[52:53], -1, 0
	s_lshl_b32 s69, s10, 1
	s_lshl_b32 s71, s11, 1
	s_mov_b32 s89, 0
	s_movk_i32 s8, 0x1020
	s_mul_i32 s12, s88, 0x1020
	s_add_i32 s70, s69, 0
	s_add_i32 s72, s71, 0
	v_mad_u32_u24 v143, v170, s8, 0
	s_lshl_b64 s[8:9], s[88:89], 12
	s_add_i32 s73, s70, 0x17c00
	s_add_i32 s74, s72, 0x13800
	s_add_i32 s10, s12, 0
	s_waitcnt vmcnt(15)
	v_mov_b32_e32 v4, 0
	s_add_u32 s8, s30, s8
	v_mov_b32_e32 v175, v4
	s_addc_u32 s9, s31, s9
	v_mul_i32_i24_e32 v5, 0xffffefe8, v170
	v_lshl_add_u64 v[2:3], s[8:9], 0, v[174:175]
	s_mov_b64 s[8:9], 0x14700200
	s_mov_b64 s[24:25], -1
	v_and_b32_e32 v1, 15, v170
	v_lshrrev_b32_e32 v142, 4, v230
	v_cmp_gt_u32_e64 s[6:7], 8, v170
	v_lshlrev_b32_e32 v122, 6, v170
	v_mov_b32_e32 v123, v4
	v_add3_u32 v144, s10, v174, 4
	v_lshl_add_u64 v[124:125], v[2:3], 0, s[8:9]
	s_xor_b32 s75, s34, 0x7bf
	s_mov_b32 s76, 0xffff0000
	v_add_u32_e32 v145, v143, v5
	v_mov_b32_e32 v146, 0x1000
	v_mov_b32_e32 v147, 0x3000
	s_movk_i32 s77, 0x90
	s_lshl_b32 s78, s34, 1
	s_add_i32 s79, 0, 0x1e800
	s_movk_i32 s80, 0x120
	s_add_i32 s81, 0, 0x1c400
	s_branch .LBB0_1963
